# v3 + sample-step gate preamble: 16 serialized w_gk loads (load+vmcnt(0) ladder) issued together, one wait, same fmac order
# baseline (speedup 1.0000x reference)
; __device__ __forceinline__ float bf2f(bf16 b) { return __uint_as_float(((unsigned)b) << 16); }
; __device__ __forceinline__ float logsig(float g) { return fminf(g, 0.f) - __logf(1.0f + __expf(-fabsf(g))); }
; __device__ __forceinline__ void gla_sample_item(const Ctx& C, int item, LAS unsigned char* lds, int tid) {
;     ...
;     if (tid < 128) { float g = C.b_gk[h * 128 + tid];
; #pragma unroll
;         for (int r = 0; r < 16; ++r) g += C.GKLR[(size_t)m * 16 + r] * C.w_gk[r * 512 + h * 128 + tid];
;         av[tid] = __expf(logsig(g) * (1.0f / 16.0f)); qs[tid] = bf2f(zr[ZQ + h * 128 + tid]) * 0.08838834764831845f; kk[tid] = bf2f(zr[ZK + h * 128 + tid]); }
;     else if (tid < 384) vv[tid - 128] = bf2f(zr[ZV + h * 256 + tid - 128]);
.LBB0_322:
	s_andn2_saveexec_b64 s[18:19], s[0:1]
	s_cbranch_execz .LBB0_324
	s_lshl_b64 s[0:1], s[16:17], 6
	v_lshl_or_b32 v102, s11, 7, v162
	v_readlane_b32 s76, v237, 9
	s_add_u32 s0, s58, s0
	v_lshlrev_b32_e32 v72, 2, v102
	v_readlane_b32 s80, v237, 13
	v_readlane_b32 s81, v237, 14
	v_readlane_b32 s82, v237, 15
	v_readlane_b32 s83, v237, 16
	s_addc_u32 s1, s59, s1
	v_lshl_add_u64 v[98:99], s[80:81], 0, v[72:73]
	v_readlane_b32 s77, v237, 10
	v_readlane_b32 s78, v237, 11
	v_readlane_b32 s79, v237, 12
	global_load_dword v103, v72, s[82:83]
	global_load_dwordx4 v[68:71], v73, s[0:1] offset:48
	global_load_dwordx4 v[86:89], v73, s[0:1] offset:32
	global_load_dwordx4 v[90:93], v73, s[0:1] offset:16
	global_load_dwordx4 v[94:97], v73, s[0:1]
	global_load_dword v100, v72, s[80:81]
	s_movk_i32 s0, 0x1000
	global_load_dword v72, v72, s[80:81] offset:2048
	v_readlane_b32 s84, v237, 17
	v_readlane_b32 s85, v237, 18
	v_readlane_b32 s86, v237, 19
	v_readlane_b32 s87, v237, 20
	v_readlane_b32 s88, v237, 21
	v_readlane_b32 s89, v237, 22
	v_readlane_b32 s90, v237, 23
	v_readlane_b32 s91, v237, 24
	s_movk_i32 s0, 0x1000
	v_add_co_u32_e32 v104, vcc, s0, v98
	s_nop 1
	v_addc_co_u32_e32 v105, vcc, 0, v99, vcc
	s_movk_i32 s0, 0x2000
	v_add_co_u32_e32 v106, vcc, s0, v98
	s_nop 1
	v_addc_co_u32_e32 v107, vcc, 0, v99, vcc
	s_movk_i32 s0, 0x3000
	v_add_co_u32_e32 v108, vcc, s0, v98
	s_nop 1
	v_addc_co_u32_e32 v109, vcc, 0, v99, vcc
	s_movk_i32 s0, 0x4000
	v_add_co_u32_e32 v110, vcc, s0, v98
	s_nop 1
	v_addc_co_u32_e32 v111, vcc, 0, v99, vcc
	s_movk_i32 s0, 0x5000
	v_add_co_u32_e32 v112, vcc, s0, v98
	s_nop 1
	v_addc_co_u32_e32 v113, vcc, 0, v99, vcc
	s_movk_i32 s0, 0x6000
	v_add_co_u32_e32 v114, vcc, s0, v98
	s_nop 1
	v_addc_co_u32_e32 v115, vcc, 0, v99, vcc
	s_movk_i32 s0, 0x7000
	v_add_co_u32_e32 v116, vcc, s0, v98
	s_nop 1
	v_addc_co_u32_e32 v117, vcc, 0, v99, vcc
	global_load_dword v132, v[104:105], off
	global_load_dword v133, v[104:105], off offset:2048
	global_load_dword v134, v[106:107], off
	global_load_dword v135, v[106:107], off offset:2048
	global_load_dword v136, v[108:109], off
	global_load_dword v137, v[108:109], off offset:2048
	global_load_dword v138, v[110:111], off
	global_load_dword v139, v[110:111], off offset:2048
	global_load_dword v140, v[112:113], off
	global_load_dword v141, v[112:113], off offset:2048
	global_load_dword v142, v[114:115], off
	global_load_dword v143, v[114:115], off offset:2048
	global_load_dword v144, v[116:117], off
	global_load_dword v145, v[116:117], off offset:2048
	s_waitcnt vmcnt(0)
	v_fmac_f32_e32 v103, v94, v100
	v_fmac_f32_e32 v103, v95, v72
	v_fmac_f32_e32 v103, v96, v132
	v_fmac_f32_e32 v103, v97, v133
	v_fmac_f32_e32 v103, v90, v134
	v_fmac_f32_e32 v103, v91, v135
	v_fmac_f32_e32 v103, v92, v136
	v_fmac_f32_e32 v103, v93, v137
	v_fmac_f32_e32 v103, v86, v138
	v_fmac_f32_e32 v103, v87, v139
	v_fmac_f32_e32 v103, v88, v140
	v_fmac_f32_e32 v103, v89, v141
	v_fmac_f32_e32 v103, v68, v142
	v_fmac_f32_e32 v103, v69, v143
	v_fmac_f32_e32 v103, v70, v144
	v_fmac_f32_e32 v103, v71, v145
	s_mov_b32 s0, 0xbfb8aa3b
	v_lshlrev_b32_e32 v72, 1, v102
	v_mul_f32_e64 v69, |v103|, s0
	v_exp_f32_e32 v69, v69
	s_mov_b32 s0, 0x800000
	v_min_f32_e32 v68, 0, v103
	v_add_f32_e32 v69, 1.0, v69
	v_cmp_gt_f32_e32 vcc, s0, v69
	s_mov_b32 s0, 0x3f317217
	s_nop 0
	v_cndmask_b32_e64 v70, 0, 32, vcc
	v_ldexp_f32 v69, v69, v70
	v_log_f32_e32 v69, v69
	s_nop 0
	v_mul_f32_e32 v70, 0x3f317217, v69
	v_fma_f32 v70, v69, s0, -v70
	v_fmac_f32_e32 v70, 0x3377d1cf, v69
	s_mov_b32 s0, 0x7f800000
	v_fmac_f32_e32 v70, 0x3f317217, v69
	v_cmp_lt_f32_e64 s[0:1], |v69|, s0
	s_nop 1
	v_cndmask_b32_e64 v69, v69, v70, s[0:1]
	v_cndmask_b32_e32 v70, 0, v84, vcc
	v_sub_f32_e32 v69, v69, v70
	v_sub_f32_e32 v68, v68, v69
	v_mul_f32_e32 v68, 0x3d800000, v68
	v_mul_f32_e32 v68, 0x3fb8aa3b, v68
	v_exp_f32_e32 v70, v68
	v_lshl_add_u64 v[68:69], s[20:21], 0, v[72:73]
	v_add_co_u32_e32 v68, vcc, 0x1000, v68
	s_nop 1
	v_addc_co_u32_e32 v69, vcc, 0, v69, vcc
	global_load_ushort v71, v[68:69], off offset:2048
	s_waitcnt vmcnt(0)
	v_lshlrev_b32_e32 v71, 16, v71
	global_load_ushort v68, v[68:69], off offset:3072
	v_mul_f32_e32 v71, 0x3db504f3, v71
	ds_write2st64_b32 v164, v70, v71 offset1:2
	s_waitcnt vmcnt(0)
	v_lshlrev_b32_e32 v68, 16, v68
	ds_write_b32 v164, v68 offset:1024

; __device__ __forceinline__ float bf2f(bf16 b) { return __uint_as_float(((unsigned)b) << 16); }
; __device__ __forceinline__ float logsig(float g) { return fminf(g, 0.f) - __logf(1.0f + __expf(-fabsf(g))); }
; __device__ __forceinline__ void gla_sample_item(const Ctx& C, int item, LAS unsigned char* lds, int tid) {
;     ...
;     if (tid < 128) { float g = C.b_gk[h * 128 + tid];
; #pragma unroll
;         for (int r = 0; r < 16; ++r) g += C.GKLR[(size_t)m * 16 + r] * C.w_gk[r * 512 + h * 128 + tid];
;         av[tid] = __expf(logsig(g) * (1.0f / 16.0f)); qs[tid] = bf2f(zr[ZQ + h * 128 + tid]) * 0.08838834764831845f; kk[tid] = bf2f(zr[ZK + h * 128 + tid]); }
;     else if (tid < 384) vv[tid - 128] = bf2f(zr[ZV + h * 256 + tid - 128]);
.LBB0_357:
	s_andn2_saveexec_b64 s[16:17], s[0:1]
	s_cbranch_execz .LBB0_359
	s_lshl_b64 s[0:1], s[14:15], 6
	v_lshl_or_b32 v102, s24, 7, v162
	v_readlane_b32 s76, v237, 9
	s_add_u32 s0, s12, s0
	v_lshlrev_b32_e32 v72, 2, v102
	v_readlane_b32 s80, v237, 13
	v_readlane_b32 s81, v237, 14
	v_readlane_b32 s82, v237, 15
	v_readlane_b32 s83, v237, 16
	s_addc_u32 s1, s13, s1
	v_lshl_add_u64 v[98:99], s[80:81], 0, v[72:73]
	v_readlane_b32 s77, v237, 10
	v_readlane_b32 s78, v237, 11
	v_readlane_b32 s79, v237, 12
	global_load_dword v103, v72, s[82:83]
	global_load_dwordx4 v[68:71], v73, s[0:1] offset:48
	global_load_dwordx4 v[86:89], v73, s[0:1] offset:32
	global_load_dwordx4 v[90:93], v73, s[0:1] offset:16
	global_load_dwordx4 v[94:97], v73, s[0:1]
	global_load_dword v100, v72, s[80:81]
	s_movk_i32 s0, 0x1000
	global_load_dword v72, v72, s[80:81] offset:2048
	v_readlane_b32 s84, v237, 17
	v_readlane_b32 s85, v237, 18
	v_readlane_b32 s86, v237, 19
	v_readlane_b32 s87, v237, 20
	v_readlane_b32 s88, v237, 21
	v_readlane_b32 s89, v237, 22
	v_readlane_b32 s90, v237, 23
	v_readlane_b32 s91, v237, 24
	s_movk_i32 s0, 0x1000
	v_add_co_u32_e32 v104, vcc, s0, v98
	s_nop 1
	v_addc_co_u32_e32 v105, vcc, 0, v99, vcc
	s_movk_i32 s0, 0x2000
	v_add_co_u32_e32 v106, vcc, s0, v98
	s_nop 1
	v_addc_co_u32_e32 v107, vcc, 0, v99, vcc
	s_movk_i32 s0, 0x3000
	v_add_co_u32_e32 v108, vcc, s0, v98
	s_nop 1
	v_addc_co_u32_e32 v109, vcc, 0, v99, vcc
	s_movk_i32 s0, 0x4000
	v_add_co_u32_e32 v110, vcc, s0, v98
	s_nop 1
	v_addc_co_u32_e32 v111, vcc, 0, v99, vcc
	s_movk_i32 s0, 0x5000
	v_add_co_u32_e32 v112, vcc, s0, v98
	s_nop 1
	v_addc_co_u32_e32 v113, vcc, 0, v99, vcc
	s_movk_i32 s0, 0x6000
	v_add_co_u32_e32 v114, vcc, s0, v98
	s_nop 1
	v_addc_co_u32_e32 v115, vcc, 0, v99, vcc
	s_movk_i32 s0, 0x7000
	v_add_co_u32_e32 v116, vcc, s0, v98
	s_nop 1
	v_addc_co_u32_e32 v117, vcc, 0, v99, vcc
	global_load_dword v132, v[104:105], off
	global_load_dword v133, v[104:105], off offset:2048
	global_load_dword v134, v[106:107], off
	global_load_dword v135, v[106:107], off offset:2048
	global_load_dword v136, v[108:109], off
	global_load_dword v137, v[108:109], off offset:2048
	global_load_dword v138, v[110:111], off
	global_load_dword v139, v[110:111], off offset:2048
	global_load_dword v140, v[112:113], off
	global_load_dword v141, v[112:113], off offset:2048
	global_load_dword v142, v[114:115], off
	global_load_dword v143, v[114:115], off offset:2048
	global_load_dword v144, v[116:117], off
	global_load_dword v145, v[116:117], off offset:2048
	s_waitcnt vmcnt(0)
	v_fmac_f32_e32 v103, v94, v100
	v_fmac_f32_e32 v103, v95, v72
	v_fmac_f32_e32 v103, v96, v132
	v_fmac_f32_e32 v103, v97, v133
	v_fmac_f32_e32 v103, v90, v134
	v_fmac_f32_e32 v103, v91, v135
	v_fmac_f32_e32 v103, v92, v136
	v_fmac_f32_e32 v103, v93, v137
	v_fmac_f32_e32 v103, v86, v138
	v_fmac_f32_e32 v103, v87, v139
	v_fmac_f32_e32 v103, v88, v140
	v_fmac_f32_e32 v103, v89, v141
	v_fmac_f32_e32 v103, v68, v142
	v_fmac_f32_e32 v103, v69, v143
	v_fmac_f32_e32 v103, v70, v144
	v_fmac_f32_e32 v103, v71, v145
	s_mov_b32 s0, 0xbfb8aa3b
	v_lshlrev_b32_e32 v72, 1, v102
	v_mul_f32_e64 v69, |v103|, s0
	v_exp_f32_e32 v69, v69
	s_mov_b32 s0, 0x800000
	v_min_f32_e32 v68, 0, v103
	v_add_f32_e32 v69, 1.0, v69
	v_cmp_gt_f32_e32 vcc, s0, v69
	s_mov_b32 s0, 0x3f317217
	s_nop 0
	v_cndmask_b32_e64 v70, 0, 32, vcc
	v_ldexp_f32 v69, v69, v70
	v_log_f32_e32 v69, v69
	s_nop 0
	v_mul_f32_e32 v70, 0x3f317217, v69
	v_fma_f32 v70, v69, s0, -v70
	v_fmac_f32_e32 v70, 0x3377d1cf, v69
	s_mov_b32 s0, 0x7f800000
	v_fmac_f32_e32 v70, 0x3f317217, v69
	v_cmp_lt_f32_e64 s[0:1], |v69|, s0
	s_nop 1
	v_cndmask_b32_e64 v69, v69, v70, s[0:1]
	v_cndmask_b32_e32 v70, 0, v84, vcc
	v_sub_f32_e32 v69, v69, v70
	v_sub_f32_e32 v68, v68, v69
	v_mul_f32_e32 v68, 0x3d800000, v68
	v_mul_f32_e32 v68, 0x3fb8aa3b, v68
	v_exp_f32_e32 v70, v68
	v_lshl_add_u64 v[68:69], s[18:19], 0, v[72:73]
	v_add_co_u32_e32 v68, vcc, 0x1000, v68
	s_nop 1
	v_addc_co_u32_e32 v69, vcc, 0, v69, vcc
	global_load_ushort v71, v[68:69], off offset:2048
	s_waitcnt vmcnt(0)
	v_lshlrev_b32_e32 v71, 16, v71
	global_load_ushort v68, v[68:69], off offset:3072
	v_mul_f32_e32 v71, 0x3db504f3, v71
	ds_write2st64_b32 v164, v70, v71 offset1:2
	s_waitcnt vmcnt(0)
	v_lshlrev_b32_e32 v68, 16, v68
	ds_write_b32 v164, v68 offset:1024
